# scan chunk loop: gl load issued first and counted vmcnt (16/16/11) instead of three vmcnt(0) drains; on top of attention loop with next-block row max precomputed in the PV section
# speedup vs baseline: 1.0078x; 1.0078x over previous
.LBB0_1295:
	s_lshl_b32 s12, s15, 6
	s_cmp_eq_u32 s26, 0
	s_cselect_b64 vcc, -1, 0
	s_and_b64 s[26:27], vcc, exec
	s_mov_b32 s13, 0x36a00000
	s_cselect_b32 s13, s13, 0x38200000
	s_add_u32 s13, s10, s13
	s_addc_u32 s30, s11, 0
	s_mul_i32 s26, s25, 0x16800
	s_mul_hi_i32 s15, s25, 0x16800
	s_add_u32 s31, s16, s26
	s_addc_u32 s34, s17, s15
	s_lshl_b32 s14, s14, 10
	s_ashr_i32 s15, s14, 31
	s_add_u32 s26, s31, s14
	s_addc_u32 s27, s34, s15
	v_lshl_add_u64 v[34:35], s[26:27], 0, v[68:69]
	s_add_i32 s26, s2, s14
	s_mov_b32 m0, s26
	s_mov_b64 s[28:29], 0x2000
	s_barrier
	global_load_lds_dwordx4 v[34:35], off
	v_lshl_add_u64 v[36:37], v[34:35], 0, s[28:29]
	s_add_i32 m0, s26, 0x2000
	s_mov_b64 s[28:29], 0x4000
	global_load_lds_dwordx4 v[36:37], off
	v_lshl_add_u64 v[36:37], v[34:35], 0, s[28:29]
	s_add_i32 m0, s26, 0x4000
	s_mov_b64 s[28:29], 0x6000
	global_load_lds_dwordx4 v[36:37], off
	v_lshl_add_u64 v[36:37], v[34:35], 0, s[28:29]
	s_add_i32 m0, s26, 0x6000
	s_mov_b64 s[28:29], 0x8000
	global_load_lds_dwordx4 v[36:37], off
	v_lshl_add_u64 v[36:37], v[34:35], 0, s[28:29]
	s_add_i32 m0, s26, 0x8000
	s_mov_b64 s[28:29], 0xa000
	global_load_lds_dwordx4 v[36:37], off
	v_lshl_add_u64 v[36:37], v[34:35], 0, s[28:29]
	s_add_i32 m0, s26, 0xa000
	s_mov_b64 s[28:29], 0xc000
	global_load_lds_dwordx4 v[36:37], off
	s_add_i32 m0, s26, 0xc000
	v_or_b32_e32 v74, s14, v85
	v_lshl_add_u64 v[34:35], v[34:35], 0, s[28:29]
	s_add_u32 s28, s31, 0xe000
	v_or_b32_e32 v76, 0x100, v74
	s_addc_u32 s29, s34, 0
	v_ashrrev_i32_e32 v75, 31, v74
	v_ashrrev_i32_e32 v77, 31, v76
	v_or_b32_e32 v78, 0x200, v74
	v_or_b32_e32 v80, 0x300, v74
	global_load_lds_dwordx4 v[34:35], off
	v_lshl_add_u64 v[34:35], v[74:75], 2, s[28:29]
	v_lshl_add_u64 v[36:37], v[76:77], 2, s[28:29]
	v_ashrrev_i32_e32 v79, 31, v78
	v_ashrrev_i32_e32 v81, 31, v80
	global_load_dwordx4 v[46:49], v[34:35], off
	global_load_dwordx4 v[42:45], v[36:37], off
	v_lshl_add_u64 v[34:35], v[78:79], 2, s[28:29]
	v_lshl_add_u64 v[36:37], v[80:81], 2, s[28:29]
	global_load_dwordx4 v[38:41], v[34:35], off
	s_nop 0
	global_load_dwordx4 v[34:37], v[36:37], off
	s_lshl_b32 s0, s0, 9
	s_add_u32 s28, s13, s0
	s_addc_u32 s29, s30, 0
	s_mov_b32 s27, 0
	v_lshl_add_u64 v[72:73], v[70:71], 2, s[28:29]
	s_sub_i32 s28, s12, 64
	v_mov_b32_e32 v104, v96
	s_mov_b32 s13, 0
	s_waitcnt vmcnt(0)
.LBB0_1296:
	s_add_i32 s0, s25, s13
	s_mul_hi_i32 s29, s0, 0x16800
	s_mul_i32 s0, s0, 0x16800
	s_add_u32 s30, s16, s0
	s_addc_u32 s31, s17, s29
	s_bitcmp1_b32 s13, 0
	s_cselect_b32 s0, 0xe000, 0
	s_add_i32 s13, s13, 1
	s_add_u32 s34, s30, s14
	s_addc_u32 s35, s31, s15
	s_bitcmp1_b32 s13, 0
	s_waitcnt vmcnt(16)
	v_mov_b64_e32 v[52:53], v[36:37]
	s_cselect_b32 s29, 0xe000, 0
	v_mov_b64_e32 v[50:51], v[34:35]
	v_lshl_add_u64 v[34:35], s[34:35], 0, v[68:69]
	s_mov_b64 s[34:35], 0x16800
	s_add_i32 s29, s26, s29
	s_waitcnt vmcnt(16)
	s_barrier
	global_load_dword v82, v231, s[30:31]
	v_lshl_add_u64 v[36:37], v[34:35], 0, s[34:35]
	s_mov_b32 m0, s29
	s_mov_b64 s[34:35], 0x18800
	global_load_lds_dwordx4 v[36:37], off
	v_lshl_add_u64 v[36:37], v[34:35], 0, s[34:35]
	s_add_i32 m0, s29, 0x2000
	s_mov_b64 s[34:35], 0x1a800
	global_load_lds_dwordx4 v[36:37], off
	v_lshl_add_u64 v[36:37], v[34:35], 0, s[34:35]
	s_add_i32 m0, s29, 0x4000
	s_mov_b64 s[34:35], 0x1c800
	global_load_lds_dwordx4 v[36:37], off
	v_lshl_add_u64 v[36:37], v[34:35], 0, s[34:35]
	s_add_i32 m0, s29, 0x6000
	s_mov_b64 s[34:35], 0x1e800
	global_load_lds_dwordx4 v[36:37], off
	v_lshl_add_u64 v[36:37], v[34:35], 0, s[34:35]
	s_add_i32 m0, s29, 0x8000
	s_mov_b64 s[34:35], 0x20800
	global_load_lds_dwordx4 v[36:37], off
	v_lshl_add_u64 v[36:37], v[34:35], 0, s[34:35]
	s_add_i32 m0, s29, 0xa000
	s_mov_b64 s[34:35], 0x22800
	global_load_lds_dwordx4 v[36:37], off
	s_add_i32 m0, s29, 0xc000
	v_lshl_add_u64 v[34:35], v[34:35], 0, s[34:35]
	s_add_u32 s34, s30, 0x24800
	s_addc_u32 s35, s31, 0
	v_mov_b64_e32 v[64:65], v[48:49]
	global_load_lds_dwordx4 v[34:35], off
	v_lshl_add_u64 v[34:35], v[74:75], 2, s[34:35]
	v_mov_b64_e32 v[62:63], v[46:47]
	v_mov_b64_e32 v[60:61], v[44:45]
	global_load_dwordx4 v[46:49], v[34:35], off
	v_lshl_add_u64 v[34:35], v[76:77], 2, s[34:35]
	v_mov_b64_e32 v[58:59], v[42:43]
	v_mov_b64_e32 v[56:57], v[40:41]
	global_load_dwordx4 v[42:45], v[34:35], off
	v_lshl_add_u64 v[34:35], v[78:79], 2, s[34:35]
	v_mov_b64_e32 v[54:55], v[38:39]
	global_load_dwordx4 v[38:41], v[34:35], off
	v_lshl_add_u64 v[34:35], v[80:81], 2, s[34:35]
	v_add_u32_e32 v105, s0, v95
	global_load_dwordx4 v[34:37], v[34:35], off
	s_nop 0
	ds_read_b128 v[122:125], v105
	ds_read_b128 v[126:129], v105 offset:16384
	v_cvt_pk_bf16_f32 v106, v30, v31
	v_cvt_pk_bf16_f32 v107, v32, v33
	v_cvt_pk_bf16_f32 v108, v22, v23
	v_cvt_pk_bf16_f32 v109, v24, v25
	v_cvt_pk_bf16_f32 v110, v26, v27
	v_cvt_pk_bf16_f32 v111, v28, v29
	s_waitcnt lgkmcnt(0)
	v_mfma_f32_16x16x32_bf16 v[62:65], v[122:125], v[106:109], v[62:65]
	v_cvt_pk_bf16_f32 v112, v14, v15
	v_cvt_pk_bf16_f32 v113, v16, v17
	v_cvt_pk_bf16_f32 v114, v18, v19
	v_mfma_f32_16x16x32_bf16 v[122:125], v[126:129], v[106:109], 0
	ds_read_b128 v[126:129], v105 offset:1024
	ds_read_b128 v[130:133], v105 offset:17408
	v_cvt_pk_bf16_f32 v115, v20, v21
	v_cvt_pk_bf16_f32 v116, v6, v7
	s_waitcnt lgkmcnt(0)
	v_mfma_f32_16x16x32_bf16 v[62:65], v[126:129], v[110:113], v[62:65]
	v_cvt_pk_bf16_f32 v117, v8, v9
	v_cvt_pk_bf16_f32 v118, v10, v11
	v_cvt_pk_bf16_f32 v119, v12, v13
	v_mfma_f32_16x16x32_bf16 v[122:125], v[130:133], v[110:113], v[122:125]
	ds_read_b128 v[126:129], v105 offset:8192
	ds_read_b128 v[130:133], v105 offset:24576
	v_cvt_pk_bf16_f32 v120, v2, v3
	v_cvt_pk_bf16_f32 v121, v4, v5
	s_waitcnt lgkmcnt(0)
	v_mfma_f32_16x16x32_bf16 v[62:65], v[126:129], v[114:117], v[62:65]
	s_waitcnt vmcnt(11)
	v_pk_mul_f32 v[32:33], v[32:33], v[82:83] op_sel_hi:[1,0]
	v_mfma_f32_16x16x32_bf16 v[122:125], v[130:133], v[114:117], v[122:125]
	ds_read_b128 v[126:129], v105 offset:9216
	ds_read_b128 v[130:133], v105 offset:25600
	v_pk_mul_f32 v[30:31], v[30:31], v[82:83] op_sel_hi:[1,0]
	v_pk_mul_f32 v[24:25], v[24:25], v[82:83] op_sel_hi:[1,0]
	s_waitcnt lgkmcnt(1)
	v_mfma_f32_16x16x32_bf16 v[62:65], v[126:129], v[118:121], v[62:65]
	v_mul_f32_e64 v22, v22, v82
	v_mul_f32_e64 v23, v23, v82
	v_pk_mul_f32 v[28:29], v[28:29], v[82:83] op_sel_hi:[1,0]
	v_pk_mul_f32 v[26:27], v[26:27], v[82:83] op_sel_hi:[1,0]
	s_waitcnt lgkmcnt(0)
	v_mfma_f32_16x16x32_bf16 v[122:125], v[130:133], v[118:121], v[122:125]
	ds_read_b128 v[126:129], v105 offset:2048
	ds_read_b128 v[130:133], v105 offset:18432
	v_pk_mul_f32 v[16:17], v[16:17], v[82:83] op_sel_hi:[1,0]
	v_pk_mul_f32 v[14:15], v[14:15], v[82:83] op_sel_hi:[1,0]
	s_waitcnt lgkmcnt(1)
	v_mfma_f32_16x16x32_bf16 v[58:61], v[126:129], v[106:109], v[58:61]
	v_mul_f32_e64 v20, v20, v82
	v_mul_f32_e64 v21, v21, v82
	v_pk_mul_f32 v[18:19], v[18:19], v[82:83] op_sel_hi:[1,0]
	v_pk_mul_f32 v[8:9], v[8:9], v[82:83] op_sel_hi:[1,0]
	s_waitcnt lgkmcnt(0)
	v_mfma_f32_16x16x32_bf16 v[126:129], v[130:133], v[106:109], 0
	ds_read_b128 v[130:133], v105 offset:3072
	ds_read_b128 v[134:137], v105 offset:19456
	v_pk_mul_f32 v[6:7], v[6:7], v[82:83] op_sel_hi:[1,0]
	v_pk_mul_f32 v[12:13], v[12:13], v[82:83] op_sel_hi:[1,0]
	s_waitcnt lgkmcnt(1)
	v_mfma_f32_16x16x32_bf16 v[58:61], v[130:133], v[110:113], v[58:61]
	v_mul_f32_e64 v10, v10, v82
	v_mul_f32_e64 v11, v11, v82
	v_pk_mul_f32 v[4:5], v[4:5], v[82:83] op_sel_hi:[1,0]
	v_pk_mul_f32 v[2:3], v[2:3], v[82:83] op_sel_hi:[1,0]
	s_waitcnt lgkmcnt(0)
	v_mfma_f32_16x16x32_bf16 v[126:129], v[134:137], v[110:113], v[126:129]
	ds_read_b128 v[130:133], v105 offset:10240
	ds_read_b128 v[134:137], v105 offset:26624
	v_add_u32_e32 v82, s27, v84
	s_add_i32 s27, s27, 64
	s_waitcnt lgkmcnt(1)
	v_mfma_f32_16x16x32_bf16 v[58:61], v[130:133], v[114:117], v[58:61]
	s_cmp_eq_u32 s28, s27
	s_waitcnt lgkmcnt(0)
	v_mfma_f32_16x16x32_bf16 v[126:129], v[134:137], v[114:117], v[126:129]
	ds_read_b128 v[130:133], v105 offset:11264
	ds_read_b128 v[134:137], v105 offset:27648
	s_waitcnt lgkmcnt(1)
	v_mfma_f32_16x16x32_bf16 v[58:61], v[130:133], v[118:121], v[58:61]
	s_waitcnt lgkmcnt(0)
	v_mfma_f32_16x16x32_bf16 v[126:129], v[134:137], v[118:121], v[126:129]
	ds_read_b128 v[130:133], v105 offset:4096
	ds_read_b128 v[134:137], v105 offset:20480
	s_waitcnt lgkmcnt(1)
	v_mfma_f32_16x16x32_bf16 v[54:57], v[130:133], v[106:109], v[54:57]
	s_waitcnt lgkmcnt(0)
	v_mfma_f32_16x16x32_bf16 v[130:133], v[134:137], v[106:109], 0
	ds_read_b128 v[134:137], v105 offset:5120
	ds_read_b128 v[138:141], v105 offset:21504
	s_waitcnt lgkmcnt(1)
	v_mfma_f32_16x16x32_bf16 v[54:57], v[134:137], v[110:113], v[54:57]
	s_waitcnt lgkmcnt(0)
	v_mfma_f32_16x16x32_bf16 v[130:133], v[138:141], v[110:113], v[130:133]
	ds_read_b128 v[134:137], v105 offset:12288
	ds_read_b128 v[138:141], v105 offset:28672
	s_waitcnt lgkmcnt(1)
	v_mfma_f32_16x16x32_bf16 v[54:57], v[134:137], v[114:117], v[54:57]
	s_waitcnt lgkmcnt(0)
	v_mfma_f32_16x16x32_bf16 v[130:133], v[138:141], v[114:117], v[130:133]
	ds_read_b128 v[134:137], v105 offset:13312
	ds_read_b128 v[138:141], v105 offset:29696
	s_waitcnt lgkmcnt(1)
	v_mfma_f32_16x16x32_bf16 v[54:57], v[134:137], v[118:121], v[54:57]
	s_waitcnt lgkmcnt(0)
	v_mfma_f32_16x16x32_bf16 v[130:133], v[138:141], v[118:121], v[130:133]
	ds_read_b128 v[134:137], v105 offset:6144
	ds_read_b128 v[138:141], v105 offset:22528
	s_waitcnt lgkmcnt(1)
	v_mfma_f32_16x16x32_bf16 v[50:53], v[134:137], v[106:109], v[50:53]
	s_waitcnt lgkmcnt(0)
	v_mfma_f32_16x16x32_bf16 v[106:109], v[138:141], v[106:109], 0
	ds_read_b128 v[134:137], v105 offset:7168
	ds_read_b128 v[138:141], v105 offset:23552
	s_waitcnt lgkmcnt(1)
	v_mfma_f32_16x16x32_bf16 v[50:53], v[134:137], v[110:113], v[50:53]
	s_waitcnt lgkmcnt(0)
	v_mfma_f32_16x16x32_bf16 v[106:109], v[138:141], v[110:113], v[106:109]
	ds_read_b128 v[110:113], v105 offset:14336
	ds_read_b128 v[134:137], v105 offset:30720
	s_waitcnt lgkmcnt(1)
	v_mfma_f32_16x16x32_bf16 v[50:53], v[110:113], v[114:117], v[50:53]
	s_waitcnt lgkmcnt(0)
	v_mfma_f32_16x16x32_bf16 v[106:109], v[134:137], v[114:117], v[106:109]
	ds_read_b128 v[110:113], v105 offset:15360
	ds_read_b128 v[114:117], v105 offset:31744
	s_waitcnt lgkmcnt(1)
	v_mfma_f32_16x16x32_bf16 v[50:53], v[110:113], v[118:121], v[50:53]
	v_cvt_pk_bf16_f32 v110, v62, v63
	v_cvt_pk_bf16_f32 v111, v64, v65
	v_cvt_pk_bf16_f32 v112, v58, v59
	s_waitcnt lgkmcnt(0)
	v_mfma_f32_16x16x32_bf16 v[106:109], v[114:117], v[118:121], v[106:109]
	s_nop 2
	v_cvt_pk_bf16_f32 v116, v50, v51
	v_cvt_pk_bf16_f32 v117, v52, v53
	ds_read_b128 v[50:53], v105 offset:49152
	v_cvt_pk_bf16_f32 v114, v54, v55
	v_cvt_pk_bf16_f32 v115, v56, v57
	ds_read_b128 v[54:57], v105 offset:50176
	v_cvt_pk_bf16_f32 v113, v60, v61
	s_waitcnt lgkmcnt(1)
	s_nop 0
	v_mfma_f32_16x16x32_bf16 v[50:53], v[50:53], v[110:113], v[122:125]
	s_waitcnt lgkmcnt(0)
	v_mfma_f32_16x16x32_bf16 v[62:65], v[54:57], v[114:117], v[50:53]
	ds_read_b128 v[54:57], v105 offset:52224
	s_nop 4
	ds_read_b128 v[50:53], v105 offset:51200
	s_waitcnt lgkmcnt(0)
	v_mfma_f32_16x16x32_bf16 v[50:53], v[50:53], v[110:113], v[126:129]
	v_mfma_f32_16x16x32_bf16 v[58:61], v[54:57], v[114:117], v[50:53]
	ds_read_b128 v[54:57], v105 offset:54272
	s_nop 5
	ds_read_b128 v[50:53], v105 offset:53248
	s_waitcnt lgkmcnt(0)
	v_mfma_f32_16x16x32_bf16 v[50:53], v[50:53], v[110:113], v[130:133]
	v_mfma_f32_16x16x32_bf16 v[54:57], v[54:57], v[114:117], v[50:53]
	s_nop 6
	ds_read_b128 v[50:53], v105 offset:55296
	s_waitcnt lgkmcnt(0)
	v_mfma_f32_16x16x32_bf16 v[50:53], v[50:53], v[110:113], v[106:109]
	s_nop 2
	ds_read_b128 v[106:109], v105 offset:56320
	s_waitcnt lgkmcnt(0)
	v_mfma_f32_16x16x32_bf16 v[50:53], v[106:109], v[114:117], v[50:53]
	ds_read_b128 v[106:109], v105 offset:32768
	s_waitcnt lgkmcnt(0)
	v_mfma_f32_16x16x32_bf16 v[30:33], v[106:109], v[110:113], v[30:33]
	ds_read_b128 v[106:109], v105 offset:33792
	s_waitcnt lgkmcnt(0)
	v_mfma_f32_16x16x32_bf16 v[30:33], v[106:109], v[114:117], v[30:33]
	ds_read_b128 v[106:109], v105 offset:34816
	s_waitcnt lgkmcnt(0)
	v_mfma_f32_16x16x32_bf16 v[22:25], v[106:109], v[110:113], v[22:25]
	ds_read_b128 v[106:109], v105 offset:35840
	s_waitcnt lgkmcnt(0)
	v_mfma_f32_16x16x32_bf16 v[22:25], v[106:109], v[114:117], v[22:25]
	ds_read_b128 v[106:109], v105 offset:36864
	s_waitcnt lgkmcnt(0)
	v_mfma_f32_16x16x32_bf16 v[26:29], v[106:109], v[110:113], v[26:29]
	ds_read_b128 v[106:109], v105 offset:37888
	s_waitcnt lgkmcnt(0)
	v_mfma_f32_16x16x32_bf16 v[26:29], v[106:109], v[114:117], v[26:29]
	ds_read_b128 v[106:109], v105 offset:38912
	s_waitcnt lgkmcnt(0)
	v_mfma_f32_16x16x32_bf16 v[14:17], v[106:109], v[110:113], v[14:17]
	ds_read_b128 v[106:109], v105 offset:39936
	s_waitcnt lgkmcnt(0)
	v_mfma_f32_16x16x32_bf16 v[14:17], v[106:109], v[114:117], v[14:17]
	ds_read_b128 v[106:109], v105 offset:40960
	s_waitcnt lgkmcnt(0)
	v_mfma_f32_16x16x32_bf16 v[18:21], v[106:109], v[110:113], v[18:21]
	ds_read_b128 v[106:109], v105 offset:41984
	s_waitcnt lgkmcnt(0)
	v_mfma_f32_16x16x32_bf16 v[18:21], v[106:109], v[114:117], v[18:21]
	ds_read_b128 v[106:109], v105 offset:43008
	s_waitcnt lgkmcnt(0)
	v_mfma_f32_16x16x32_bf16 v[6:9], v[106:109], v[110:113], v[6:9]
	ds_read_b128 v[106:109], v105 offset:44032
	s_waitcnt lgkmcnt(0)
	v_mfma_f32_16x16x32_bf16 v[6:9], v[106:109], v[114:117], v[6:9]
	ds_read_b128 v[106:109], v105 offset:45056
	s_waitcnt lgkmcnt(0)
	v_mfma_f32_16x16x32_bf16 v[10:13], v[106:109], v[110:113], v[10:13]
	ds_read_b128 v[106:109], v105 offset:46080
	s_waitcnt lgkmcnt(0)
	v_mfma_f32_16x16x32_bf16 v[10:13], v[106:109], v[114:117], v[10:13]
	ds_read_b128 v[106:109], v105 offset:47104
	s_waitcnt lgkmcnt(0)
	v_mfma_f32_16x16x32_bf16 v[2:5], v[106:109], v[110:113], v[2:5]
	ds_read_b128 v[106:109], v105 offset:48128
	v_add3_u32 v105, s28, v104, 63
	v_cndmask_b32_e32 v105, v105, v82, vcc
	s_waitcnt lgkmcnt(0)
	v_mfma_f32_16x16x32_bf16 v[2:5], v[106:109], v[114:117], v[2:5]
	v_add_u32_e32 v106, s24, v105
	v_ashrrev_i32_e32 v107, 31, v106
	v_lshlrev_b64 v[106:107], 11, v[106:107]
	v_lshl_add_u64 v[106:107], v[72:73], 0, v[106:107]
	global_store_dword v[106:107], v62, off
	v_add_u32_e32 v62, 1, v82
	v_xad_u32 v105, v82, -2, s12
	v_cndmask_b32_e32 v62, v105, v62, vcc
	v_add_u32_e32 v106, s24, v62
	v_ashrrev_i32_e32 v107, 31, v106
	v_lshlrev_b64 v[106:107], 11, v[106:107]
	v_lshl_add_u64 v[106:107], v[72:73], 0, v[106:107]
	global_store_dword v[106:107], v63, off
	v_add_u32_e32 v62, 2, v82
	v_xad_u32 v63, v82, -3, s12
	v_cndmask_b32_e32 v62, v63, v62, vcc
	v_add_u32_e32 v62, s24, v62
	v_ashrrev_i32_e32 v63, 31, v62
	v_lshlrev_b64 v[62:63], 11, v[62:63]
	v_lshl_add_u64 v[62:63], v[72:73], 0, v[62:63]
	global_store_dword v[62:63], v64, off
	v_add_u32_e32 v62, 3, v82
	v_xad_u32 v63, v82, -4, s12
	v_cndmask_b32_e32 v62, v63, v62, vcc
	v_add_u32_e32 v62, s24, v62
	v_ashrrev_i32_e32 v63, 31, v62
	v_lshlrev_b64 v[62:63], 11, v[62:63]
	v_lshl_add_u64 v[62:63], v[72:73], 0, v[62:63]
	global_store_dword v[62:63], v65, off
	v_xor_b32_e32 v63, 0xffffffef, v82
	v_add_u32_e32 v62, 16, v82
	v_add_u32_e32 v63, s12, v63
	v_cndmask_b32_e32 v62, v63, v62, vcc
	v_add_u32_e32 v62, s24, v62
	v_ashrrev_i32_e32 v63, 31, v62
	v_lshlrev_b64 v[62:63], 11, v[62:63]
	v_lshl_add_u64 v[62:63], v[72:73], 0, v[62:63]
	global_store_dword v[62:63], v58, off
	v_xor_b32_e32 v62, 0xffffffee, v82
	v_add_u32_e32 v58, 17, v82
	v_add_u32_e32 v62, s12, v62
	v_cndmask_b32_e32 v58, v62, v58, vcc
	v_add_u32_e32 v62, s24, v58
	v_ashrrev_i32_e32 v63, 31, v62
	v_lshlrev_b64 v[62:63], 11, v[62:63]
	v_lshl_add_u64 v[62:63], v[72:73], 0, v[62:63]
	global_store_dword v[62:63], v59, off
	v_xor_b32_e32 v59, 0xffffffed, v82
	v_add_u32_e32 v58, 18, v82
	v_add_u32_e32 v59, s12, v59
	v_cndmask_b32_e32 v58, v59, v58, vcc
	v_add_u32_e32 v58, s24, v58
	v_ashrrev_i32_e32 v59, 31, v58
	v_lshlrev_b64 v[58:59], 11, v[58:59]
	v_lshl_add_u64 v[58:59], v[72:73], 0, v[58:59]
	global_store_dword v[58:59], v60, off
	v_xor_b32_e32 v59, 0xffffffec, v82
	v_add_u32_e32 v58, 19, v82
	v_add_u32_e32 v59, s12, v59
	v_cndmask_b32_e32 v58, v59, v58, vcc
	v_add_u32_e32 v58, s24, v58
	v_ashrrev_i32_e32 v59, 31, v58
	v_lshlrev_b64 v[58:59], 11, v[58:59]
	v_lshl_add_u64 v[58:59], v[72:73], 0, v[58:59]
	global_store_dword v[58:59], v61, off
	v_xor_b32_e32 v59, 0xffffffdf, v82
	v_add_u32_e32 v58, 32, v82
	v_add_u32_e32 v59, s12, v59
	v_cndmask_b32_e32 v58, v59, v58, vcc
	v_add_u32_e32 v58, s24, v58
	v_ashrrev_i32_e32 v59, 31, v58
	v_lshlrev_b64 v[58:59], 11, v[58:59]
	v_lshl_add_u64 v[58:59], v[72:73], 0, v[58:59]
	global_store_dword v[58:59], v54, off
	v_xor_b32_e32 v58, 0xffffffde, v82
	v_add_u32_e32 v54, 33, v82
	v_add_u32_e32 v58, s12, v58
	v_cndmask_b32_e32 v54, v58, v54, vcc
	v_add_u32_e32 v58, s24, v54
	v_ashrrev_i32_e32 v59, 31, v58
	v_lshlrev_b64 v[58:59], 11, v[58:59]
	v_lshl_add_u64 v[58:59], v[72:73], 0, v[58:59]
	global_store_dword v[58:59], v55, off
	v_xor_b32_e32 v55, 0xffffffdd, v82
	v_add_u32_e32 v54, 34, v82
	v_add_u32_e32 v55, s12, v55
	v_cndmask_b32_e32 v54, v55, v54, vcc
	v_add_u32_e32 v54, s24, v54
	v_ashrrev_i32_e32 v55, 31, v54
	v_lshlrev_b64 v[54:55], 11, v[54:55]
	v_lshl_add_u64 v[54:55], v[72:73], 0, v[54:55]
	global_store_dword v[54:55], v56, off
	v_xor_b32_e32 v55, 0xffffffdc, v82
	v_add_u32_e32 v54, 35, v82
	v_add_u32_e32 v55, s12, v55
	v_cndmask_b32_e32 v54, v55, v54, vcc
	v_add_u32_e32 v54, s24, v54
	v_ashrrev_i32_e32 v55, 31, v54
	v_lshlrev_b64 v[54:55], 11, v[54:55]
	v_lshl_add_u64 v[54:55], v[72:73], 0, v[54:55]
	global_store_dword v[54:55], v57, off
	v_xor_b32_e32 v55, 0xffffffcf, v82
	v_add_u32_e32 v54, 48, v82
	v_add_u32_e32 v55, s12, v55
	v_cndmask_b32_e32 v54, v55, v54, vcc
	v_add_u32_e32 v54, s24, v54
	v_ashrrev_i32_e32 v55, 31, v54
	v_lshlrev_b64 v[54:55], 11, v[54:55]
	v_lshl_add_u64 v[54:55], v[72:73], 0, v[54:55]
	global_store_dword v[54:55], v50, off
	v_xor_b32_e32 v54, 0xffffffce, v82
	v_add_u32_e32 v50, 49, v82
	v_add_u32_e32 v54, s12, v54
	v_cndmask_b32_e32 v50, v54, v50, vcc
	v_add_u32_e32 v54, s24, v50
	v_ashrrev_i32_e32 v55, 31, v54
	v_lshlrev_b64 v[54:55], 11, v[54:55]
	v_lshl_add_u64 v[54:55], v[72:73], 0, v[54:55]
	global_store_dword v[54:55], v51, off
	v_xor_b32_e32 v51, 0xffffffcd, v82
	v_add_u32_e32 v50, 50, v82
	v_add_u32_e32 v51, s12, v51
	v_cndmask_b32_e32 v50, v51, v50, vcc
	v_add_u32_e32 v50, s24, v50
	v_ashrrev_i32_e32 v51, 31, v50
	v_lshlrev_b64 v[50:51], 11, v[50:51]
	v_lshl_add_u64 v[50:51], v[72:73], 0, v[50:51]
	global_store_dword v[50:51], v52, off
	v_xor_b32_e32 v51, 0xffffffcc, v82
	v_add_u32_e32 v50, 51, v82
	v_add_u32_e32 v51, s12, v51
	v_cndmask_b32_e32 v50, v51, v50, vcc
	v_add_u32_e32 v50, s24, v50
	v_ashrrev_i32_e32 v51, 31, v50
	v_lshlrev_b64 v[50:51], 11, v[50:51]
	v_lshl_add_u64 v[50:51], v[72:73], 0, v[50:51]
	v_subrev_u32_e32 v104, 64, v104
	global_store_dword v[50:51], v53, off
	s_cbranch_scc0 .LBB0_1296
	s_waitcnt vmcnt(0)
	s_barrier
	v_add_u32_e32 v75, s20, v86
	ds_read_b128 v[76:79], v95 offset:57344
	ds_read_b128 v[104:107], v75
	s_add_i32 s0, s13, s25
	s_mul_hi_i32 s15, s0, 0x16800
	s_mul_i32 s0, s0, 0x16800
	s_add_u32 s14, s16, s0
	s_addc_u32 s15, s17, s15
	v_cvt_pk_bf16_f32 v62, v30, v31
	v_cvt_pk_bf16_f32 v63, v32, v33
	v_cvt_pk_bf16_f32 v64, v22, v23
	v_cvt_pk_bf16_f32 v65, v24, v25
	global_load_dword v74, v231, s[14:15]
	v_cvt_pk_bf16_f32 v58, v26, v27
	s_waitcnt lgkmcnt(1)
	v_mfma_f32_16x16x32_bf16 v[46:49], v[76:79], v[62:65], v[46:49]
	v_cvt_pk_bf16_f32 v59, v28, v29
	v_cvt_pk_bf16_f32 v60, v14, v15
	v_cvt_pk_bf16_f32 v61, v16, v17
	s_waitcnt lgkmcnt(0)
	v_mfma_f32_16x16x32_bf16 v[76:79], v[104:107], v[62:65], 0
	ds_read_b128 v[104:107], v95 offset:58368
	ds_read_b128 v[108:111], v97
	v_add_u32_e32 v75, s2, v87
	v_cvt_pk_bf16_f32 v54, v18, v19
	s_waitcnt lgkmcnt(1)
	v_mfma_f32_16x16x32_bf16 v[46:49], v[104:107], v[58:61], v[46:49]
	ds_read_b128 v[104:107], v75 offset:57344
	v_add_u32_e32 v75, s20, v87
	v_cvt_pk_bf16_f32 v55, v20, v21
	s_waitcnt lgkmcnt(1)
	v_mfma_f32_16x16x32_bf16 v[76:79], v[108:111], v[58:61], v[76:79]
	ds_read_b128 v[108:111], v75
	v_cvt_pk_bf16_f32 v56, v6, v7
	v_cvt_pk_bf16_f32 v57, v8, v9
	v_add_u32_e32 v75, s2, v88
	v_cvt_pk_bf16_f32 v50, v10, v11
	s_waitcnt lgkmcnt(1)
	v_mfma_f32_16x16x32_bf16 v[46:49], v[104:107], v[54:57], v[46:49]
	ds_read_b128 v[104:107], v75 offset:57344
	v_add_u32_e32 v75, s20, v88
	v_cvt_pk_bf16_f32 v51, v12, v13
	s_waitcnt lgkmcnt(1)
	v_mfma_f32_16x16x32_bf16 v[76:79], v[108:111], v[54:57], v[76:79]
	ds_read_b128 v[108:111], v75
	v_cvt_pk_bf16_f32 v52, v2, v3
	v_cvt_pk_bf16_f32 v53, v4, v5
	v_add_u32_e32 v75, s2, v89
	s_lshl_b32 s0, s13, 6
	s_waitcnt lgkmcnt(1)
	v_mfma_f32_16x16x32_bf16 v[104:107], v[104:107], v[50:53], v[46:49]
	s_waitcnt lgkmcnt(0)
	v_mfma_f32_16x16x32_bf16 v[46:49], v[108:111], v[50:53], v[76:79]
	s_nop 2
	ds_read_b128 v[76:79], v95 offset:59392
	ds_read_b128 v[108:111], v98
	s_waitcnt lgkmcnt(1)
	v_mfma_f32_16x16x32_bf16 v[42:45], v[76:79], v[62:65], v[42:45]
	s_waitcnt lgkmcnt(0)
	v_mfma_f32_16x16x32_bf16 v[76:79], v[108:111], v[62:65], 0
	ds_read_b128 v[108:111], v95 offset:60416
	ds_read_b128 v[112:115], v99
	s_waitcnt lgkmcnt(1)
	v_mfma_f32_16x16x32_bf16 v[42:45], v[108:111], v[58:61], v[42:45]
	ds_read_b128 v[108:111], v75 offset:57344
	v_add_u32_e32 v75, s20, v89
	s_waitcnt lgkmcnt(1)
	v_mfma_f32_16x16x32_bf16 v[76:79], v[112:115], v[58:61], v[76:79]
	ds_read_b128 v[112:115], v75
	v_add_u32_e32 v75, s2, v90
	s_waitcnt lgkmcnt(1)
	v_mfma_f32_16x16x32_bf16 v[42:45], v[108:111], v[54:57], v[42:45]
	ds_read_b128 v[108:111], v75 offset:57344
	v_add_u32_e32 v75, s20, v90
	s_waitcnt lgkmcnt(1)
	v_mfma_f32_16x16x32_bf16 v[76:79], v[112:115], v[54:57], v[76:79]
	ds_read_b128 v[112:115], v75
	v_add_u32_e32 v75, s2, v91
	s_waitcnt lgkmcnt(1)
	v_mfma_f32_16x16x32_bf16 v[42:45], v[108:111], v[50:53], v[42:45]
	s_waitcnt lgkmcnt(0)
	v_mfma_f32_16x16x32_bf16 v[76:79], v[112:115], v[50:53], v[76:79]
	ds_read_b128 v[108:111], v95 offset:61440
	ds_read_b128 v[112:115], v100
	s_waitcnt lgkmcnt(1)
	v_mfma_f32_16x16x32_bf16 v[38:41], v[108:111], v[62:65], v[38:41]
	s_waitcnt lgkmcnt(0)
	v_mfma_f32_16x16x32_bf16 v[108:111], v[112:115], v[62:65], 0
	ds_read_b128 v[112:115], v95 offset:62464
	ds_read_b128 v[116:119], v101
	s_waitcnt lgkmcnt(1)
	v_mfma_f32_16x16x32_bf16 v[38:41], v[112:115], v[58:61], v[38:41]
	ds_read_b128 v[112:115], v75 offset:57344
	v_add_u32_e32 v75, s20, v91
	s_waitcnt lgkmcnt(1)
	v_mfma_f32_16x16x32_bf16 v[108:111], v[116:119], v[58:61], v[108:111]
	ds_read_b128 v[116:119], v75
	v_add_u32_e32 v75, s2, v92
	s_waitcnt lgkmcnt(1)
	v_mfma_f32_16x16x32_bf16 v[38:41], v[112:115], v[54:57], v[38:41]
	ds_read_b128 v[112:115], v75 offset:57344
	v_add_u32_e32 v75, s20, v92
	s_waitcnt lgkmcnt(1)
	v_mfma_f32_16x16x32_bf16 v[108:111], v[116:119], v[54:57], v[108:111]
	ds_read_b128 v[116:119], v75
	v_add_u32_e32 v75, s20, v93
	s_waitcnt vmcnt(0)
	v_pk_mul_f32 v[32:33], v[32:33], v[74:75] op_sel_hi:[1,0]
	s_waitcnt lgkmcnt(1)
	v_mfma_f32_16x16x32_bf16 v[38:41], v[112:115], v[50:53], v[38:41]
	v_mul_f32_e64 v30, v30, v74
	v_mul_f32_e64 v31, v31, v74
	v_pk_mul_f32 v[24:25], v[24:25], v[74:75] op_sel_hi:[1,0]
	v_pk_mul_f32 v[22:23], v[22:23], v[74:75] op_sel_hi:[1,0]
	s_waitcnt lgkmcnt(0)
	v_mfma_f32_16x16x32_bf16 v[108:111], v[116:119], v[50:53], v[108:111]
	ds_read_b128 v[112:115], v95 offset:63488
	ds_read_b128 v[116:119], v102
	v_pk_mul_f32 v[28:29], v[28:29], v[74:75] op_sel_hi:[1,0]
	v_pk_mul_f32 v[26:27], v[26:27], v[74:75] op_sel_hi:[1,0]
	s_waitcnt lgkmcnt(1)
	v_mfma_f32_16x16x32_bf16 v[34:37], v[112:115], v[62:65], v[34:37]
	v_mul_f32_e64 v16, v16, v74
	v_mul_f32_e64 v17, v17, v74
	v_pk_mul_f32 v[14:15], v[14:15], v[74:75] op_sel_hi:[1,0]
	v_pk_mul_f32 v[20:21], v[20:21], v[74:75] op_sel_hi:[1,0]
	s_waitcnt lgkmcnt(0)
	v_mfma_f32_16x16x32_bf16 v[62:65], v[116:119], v[62:65], 0
	ds_read_b128 v[112:115], v95 offset:64512
	ds_read_b128 v[116:119], v103
	v_pk_mul_f32 v[18:19], v[18:19], v[74:75] op_sel_hi:[1,0]
	v_pk_mul_f32 v[8:9], v[8:9], v[74:75] op_sel_hi:[1,0]
	s_waitcnt lgkmcnt(1)
	v_mfma_f32_16x16x32_bf16 v[34:37], v[112:115], v[58:61], v[34:37]
	ds_read_b128 v[112:115], v75
	v_pk_mul_f32 v[6:7], v[6:7], v[74:75] op_sel_hi:[1,0]
	v_pk_mul_f32 v[12:13], v[12:13], v[74:75] op_sel_hi:[1,0]
	s_waitcnt lgkmcnt(1)
	v_mfma_f32_16x16x32_bf16 v[58:61], v[116:119], v[58:61], v[62:65]
	v_mul_f32_e64 v10, v10, v74
	v_mul_f32_e64 v11, v11, v74
	v_pk_mul_f32 v[4:5], v[4:5], v[74:75] op_sel_hi:[1,0]
	v_pk_mul_f32 v[2:3], v[2:3], v[74:75] op_sel_hi:[1,0]
	v_add_u32_e32 v62, s2, v93
	ds_read_b128 v[62:65], v62 offset:57344
	s_waitcnt lgkmcnt(0)
	v_mfma_f32_16x16x32_bf16 v[34:37], v[62:65], v[54:57], v[34:37]
	v_add_u32_e32 v62, s20, v94
	ds_read_b128 v[62:65], v62
	v_mfma_f32_16x16x32_bf16 v[54:57], v[112:115], v[54:57], v[58:61]
	s_nop 2
	v_add_u32_e32 v58, s2, v94
	ds_read_b128 v[58:61], v58 offset:57344
	s_waitcnt lgkmcnt(1)
	v_mfma_f32_16x16x32_bf16 v[54:57], v[62:65], v[50:53], v[54:57]
	v_add_u32_e32 v62, s21, v86
	s_waitcnt lgkmcnt(0)
	v_mfma_f32_16x16x32_bf16 v[34:37], v[58:61], v[50:53], v[34:37]
	v_cvt_pk_bf16_f32 v58, v38, v39
	v_cvt_pk_bf16_f32 v59, v40, v41
	ds_read_b128 v[38:41], v62 offset:1024
	s_nop 4
	v_cvt_pk_bf16_f32 v60, v34, v35
	v_cvt_pk_bf16_f32 v61, v36, v37
	ds_read_b128 v[34:37], v62
	v_cvt_pk_bf16_f32 v50, v104, v105
	v_cvt_pk_bf16_f32 v51, v106, v107
	v_cvt_pk_bf16_f32 v52, v42, v43
	v_cvt_pk_bf16_f32 v53, v44, v45
	s_waitcnt lgkmcnt(0)
	s_nop 0
	v_mfma_f32_16x16x32_bf16 v[34:37], v[34:37], v[50:53], v[46:49]
	v_mfma_f32_16x16x32_bf16 v[46:49], v[38:41], v[58:61], v[34:37]
	ds_read_b128 v[38:41], v62 offset:3072
	s_nop 5
	ds_read_b128 v[34:37], v62 offset:2048
	s_waitcnt lgkmcnt(0)
	v_mfma_f32_16x16x32_bf16 v[34:37], v[34:37], v[50:53], v[76:79]
	v_mfma_f32_16x16x32_bf16 v[42:45], v[38:41], v[58:61], v[34:37]
	ds_read_b128 v[38:41], v62 offset:5120
	s_nop 5
	ds_read_b128 v[34:37], v62 offset:4096
	s_waitcnt lgkmcnt(0)
	v_mfma_f32_16x16x32_bf16 v[34:37], v[34:37], v[50:53], v[108:111]
	v_mfma_f32_16x16x32_bf16 v[38:41], v[38:41], v[58:61], v[34:37]
	s_nop 6
	ds_read_b128 v[34:37], v62 offset:6144
	s_waitcnt lgkmcnt(0)
	v_mfma_f32_16x16x32_bf16 v[34:37], v[34:37], v[50:53], v[54:57]
	s_nop 2
	ds_read_b128 v[54:57], v62 offset:7168
	v_add_u32_e32 v62, s22, v86
	s_waitcnt lgkmcnt(0)
	v_mfma_f32_16x16x32_bf16 v[34:37], v[54:57], v[58:61], v[34:37]
	ds_read_b128 v[54:57], v62
	s_waitcnt lgkmcnt(0)
	v_mfma_f32_16x16x32_bf16 v[30:33], v[54:57], v[50:53], v[30:33]
	ds_read_b128 v[54:57], v62 offset:1024
	s_waitcnt lgkmcnt(0)
	v_mfma_f32_16x16x32_bf16 v[30:33], v[54:57], v[58:61], v[30:33]
	ds_read_b128 v[54:57], v62 offset:2048
	s_waitcnt lgkmcnt(0)
	v_mfma_f32_16x16x32_bf16 v[22:25], v[54:57], v[50:53], v[22:25]
	ds_read_b128 v[54:57], v62 offset:3072
	s_waitcnt lgkmcnt(0)
	v_mfma_f32_16x16x32_bf16 v[22:25], v[54:57], v[58:61], v[22:25]
	ds_read_b128 v[54:57], v62 offset:4096
	s_waitcnt lgkmcnt(0)
	v_mfma_f32_16x16x32_bf16 v[26:29], v[54:57], v[50:53], v[26:29]
	ds_read_b128 v[54:57], v62 offset:5120
	s_waitcnt lgkmcnt(0)
	v_mfma_f32_16x16x32_bf16 v[26:29], v[54:57], v[58:61], v[26:29]
	ds_read_b128 v[54:57], v62 offset:6144
	s_waitcnt lgkmcnt(0)
	v_mfma_f32_16x16x32_bf16 v[14:17], v[54:57], v[50:53], v[14:17]
	ds_read_b128 v[54:57], v62 offset:7168
	s_waitcnt lgkmcnt(0)
	v_mfma_f32_16x16x32_bf16 v[14:17], v[54:57], v[58:61], v[14:17]
	ds_read_b128 v[54:57], v62 offset:8192
	s_waitcnt lgkmcnt(0)
	v_mfma_f32_16x16x32_bf16 v[18:21], v[54:57], v[50:53], v[18:21]
	ds_read_b128 v[54:57], v62 offset:9216
	s_waitcnt lgkmcnt(0)
	v_mfma_f32_16x16x32_bf16 v[18:21], v[54:57], v[58:61], v[18:21]
	ds_read_b128 v[54:57], v62 offset:10240
	s_waitcnt lgkmcnt(0)
	v_mfma_f32_16x16x32_bf16 v[6:9], v[54:57], v[50:53], v[6:9]
	ds_read_b128 v[54:57], v62 offset:11264
	s_waitcnt lgkmcnt(0)
	v_mfma_f32_16x16x32_bf16 v[6:9], v[54:57], v[58:61], v[6:9]
	ds_read_b128 v[54:57], v62 offset:12288
	s_waitcnt lgkmcnt(0)
	v_mfma_f32_16x16x32_bf16 v[10:13], v[54:57], v[50:53], v[10:13]
	ds_read_b128 v[54:57], v62 offset:13312
	s_waitcnt lgkmcnt(0)
	v_mfma_f32_16x16x32_bf16 v[10:13], v[54:57], v[58:61], v[10:13]
	ds_read_b128 v[54:57], v62 offset:14336
	s_waitcnt lgkmcnt(0)
	v_mfma_f32_16x16x32_bf16 v[2:5], v[54:57], v[50:53], v[2:5]
	ds_read_b128 v[50:53], v62 offset:15360
	s_waitcnt lgkmcnt(0)
	v_mfma_f32_16x16x32_bf16 v[2:5], v[50:53], v[58:61], v[2:5]
	v_or_b32_e32 v52, s0, v84
	v_xad_u32 v50, v52, -1, s12
	v_cndmask_b32_e32 v50, v50, v52, vcc
	v_add_u32_e32 v50, s24, v50
	v_ashrrev_i32_e32 v51, 31, v50
	v_lshlrev_b64 v[50:51], 11, v[50:51]
	v_lshl_add_u64 v[50:51], v[72:73], 0, v[50:51]
	global_store_dword v[50:51], v46, off
	v_or_b32_e32 v46, 1, v52
	v_xad_u32 v50, v52, -2, s12
	v_cndmask_b32_e32 v46, v50, v46, vcc
	v_add_u32_e32 v50, s24, v46
	v_ashrrev_i32_e32 v51, 31, v50
	v_lshlrev_b64 v[50:51], 11, v[50:51]
	v_lshl_add_u64 v[50:51], v[72:73], 0, v[50:51]
	global_store_dword v[50:51], v47, off
	v_or_b32_e32 v46, 2, v52
	v_xad_u32 v47, v52, -3, s12
	v_cndmask_b32_e32 v46, v47, v46, vcc
	v_add_u32_e32 v46, s24, v46
	v_ashrrev_i32_e32 v47, 31, v46
	v_lshlrev_b64 v[46:47], 11, v[46:47]
	v_lshl_add_u64 v[46:47], v[72:73], 0, v[46:47]
	global_store_dword v[46:47], v48, off
	v_or_b32_e32 v46, 3, v52
	v_xad_u32 v47, v52, -4, s12
	v_cndmask_b32_e32 v46, v47, v46, vcc
	v_add_u32_e32 v46, s24, v46
	v_ashrrev_i32_e32 v47, 31, v46
	v_lshlrev_b64 v[46:47], 11, v[46:47]
	v_lshl_add_u64 v[46:47], v[72:73], 0, v[46:47]
	global_store_dword v[46:47], v49, off
	v_not_b32_e32 v47, 16
	v_bitop3_b32 v47, s0, v47, v84 bitop3:0x36
	v_or_b32_e32 v46, 16, v52
	v_add_u32_e32 v47, s12, v47
	v_cndmask_b32_e32 v46, v47, v46, vcc
	v_add_u32_e32 v46, s24, v46
	v_ashrrev_i32_e32 v47, 31, v46
	v_lshlrev_b64 v[46:47], 11, v[46:47]
	v_lshl_add_u64 v[46:47], v[72:73], 0, v[46:47]
	global_store_dword v[46:47], v42, off
	v_not_b32_e32 v46, 17
	v_bitop3_b32 v46, s0, v46, v84 bitop3:0x36
	v_or_b32_e32 v42, 17, v52
	v_add_u32_e32 v46, s12, v46
	v_cndmask_b32_e32 v42, v46, v42, vcc
	v_add_u32_e32 v46, s24, v42
	v_ashrrev_i32_e32 v47, 31, v46
	v_lshlrev_b64 v[46:47], 11, v[46:47]
	v_lshl_add_u64 v[46:47], v[72:73], 0, v[46:47]
	global_store_dword v[46:47], v43, off
	v_not_b32_e32 v43, 18
	v_bitop3_b32 v43, s0, v43, v84 bitop3:0x36
	v_or_b32_e32 v42, 18, v52
	v_add_u32_e32 v43, s12, v43
	v_cndmask_b32_e32 v42, v43, v42, vcc
	v_add_u32_e32 v42, s24, v42
	v_ashrrev_i32_e32 v43, 31, v42
	v_lshlrev_b64 v[42:43], 11, v[42:43]
	v_lshl_add_u64 v[42:43], v[72:73], 0, v[42:43]
	global_store_dword v[42:43], v44, off
	v_not_b32_e32 v43, 19
	v_bitop3_b32 v43, s0, v43, v84 bitop3:0x36
	v_or_b32_e32 v42, 19, v52
	v_add_u32_e32 v43, s12, v43
	v_cndmask_b32_e32 v42, v43, v42, vcc
	v_add_u32_e32 v42, s24, v42
	v_ashrrev_i32_e32 v43, 31, v42
	v_lshlrev_b64 v[42:43], 11, v[42:43]
	v_lshl_add_u64 v[42:43], v[72:73], 0, v[42:43]
	global_store_dword v[42:43], v45, off
	v_not_b32_e32 v43, 32
	v_bitop3_b32 v43, s0, v43, v84 bitop3:0x36
	v_or_b32_e32 v42, 32, v52
	v_add_u32_e32 v43, s12, v43
	v_cndmask_b32_e32 v42, v43, v42, vcc
	v_add_u32_e32 v42, s24, v42
	v_ashrrev_i32_e32 v43, 31, v42
	v_lshlrev_b64 v[42:43], 11, v[42:43]
	v_lshl_add_u64 v[42:43], v[72:73], 0, v[42:43]
	global_store_dword v[42:43], v38, off
	v_not_b32_e32 v42, 33
	v_bitop3_b32 v42, s0, v42, v84 bitop3:0x36
	v_or_b32_e32 v38, 33, v52
	v_add_u32_e32 v42, s12, v42
	v_cndmask_b32_e32 v38, v42, v38, vcc
	v_add_u32_e32 v42, s24, v38
	v_ashrrev_i32_e32 v43, 31, v42
	v_lshlrev_b64 v[42:43], 11, v[42:43]
	v_lshl_add_u64 v[42:43], v[72:73], 0, v[42:43]
	global_store_dword v[42:43], v39, off
	v_not_b32_e32 v39, 34
	v_bitop3_b32 v39, s0, v39, v84 bitop3:0x36
	v_or_b32_e32 v38, 34, v52
	v_add_u32_e32 v39, s12, v39
	v_cndmask_b32_e32 v38, v39, v38, vcc
	v_add_u32_e32 v38, s24, v38
	v_ashrrev_i32_e32 v39, 31, v38
	v_lshlrev_b64 v[38:39], 11, v[38:39]
	v_lshl_add_u64 v[38:39], v[72:73], 0, v[38:39]
	global_store_dword v[38:39], v40, off
	v_not_b32_e32 v39, 35
	v_bitop3_b32 v39, s0, v39, v84 bitop3:0x36
	v_or_b32_e32 v38, 35, v52
	v_add_u32_e32 v39, s12, v39
	v_cndmask_b32_e32 v38, v39, v38, vcc
	v_add_u32_e32 v38, s24, v38
	v_ashrrev_i32_e32 v39, 31, v38
	v_lshlrev_b64 v[38:39], 11, v[38:39]
	v_lshl_add_u64 v[38:39], v[72:73], 0, v[38:39]
	global_store_dword v[38:39], v41, off
	v_not_b32_e32 v39, 48
	v_bitop3_b32 v39, s0, v39, v84 bitop3:0x36
	v_or_b32_e32 v38, 48, v52
	v_add_u32_e32 v39, s12, v39
	v_cndmask_b32_e32 v38, v39, v38, vcc
	v_add_u32_e32 v38, s24, v38
	v_ashrrev_i32_e32 v39, 31, v38
	v_lshlrev_b64 v[38:39], 11, v[38:39]
	v_lshl_add_u64 v[38:39], v[72:73], 0, v[38:39]
	global_store_dword v[38:39], v34, off
	v_not_b32_e32 v38, 49
	v_bitop3_b32 v38, s0, v38, v84 bitop3:0x36
	v_or_b32_e32 v34, 49, v52
	v_add_u32_e32 v38, s12, v38
	v_cndmask_b32_e32 v34, v38, v34, vcc
	v_add_u32_e32 v38, s24, v34
	v_ashrrev_i32_e32 v39, 31, v38
	v_lshlrev_b64 v[38:39], 11, v[38:39]
	v_lshl_add_u64 v[38:39], v[72:73], 0, v[38:39]
	global_store_dword v[38:39], v35, off
	v_not_b32_e32 v35, 50
	v_bitop3_b32 v35, s0, v35, v84 bitop3:0x36
	v_or_b32_e32 v34, 50, v52
	v_add_u32_e32 v35, s12, v35
	v_cndmask_b32_e32 v34, v35, v34, vcc
	v_add_u32_e32 v34, s24, v34
	v_ashrrev_i32_e32 v35, 31, v34
	v_lshlrev_b64 v[34:35], 11, v[34:35]
	v_lshl_add_u64 v[34:35], v[72:73], 0, v[34:35]
	global_store_dword v[34:35], v36, off
	v_not_b32_e32 v35, 51
	v_bitop3_b32 v35, s0, v35, v84 bitop3:0x36
	v_or_b32_e32 v34, 51, v52
	v_add_u32_e32 v35, s12, v35
	v_cndmask_b32_e32 v34, v35, v34, vcc
	v_add_u32_e32 v34, s24, v34
	v_ashrrev_i32_e32 v35, 31, v34
	v_lshlrev_b64 v[34:35], 11, v[34:35]
	v_lshl_add_u64 v[34:35], v[72:73], 0, v[34:35]
	s_andn2_b64 vcc, exec, s[6:7]
	global_store_dword v[34:35], v37, off
	s_cbranch_vccnz .LBB0_1288
	s_lshl_b64 s[6:7], s[8:9], 2
	s_add_u32 s6, s18, s6
	s_addc_u32 s7, s19, s7
	v_lshl_add_u64 v[34:35], v[70:71], 2, s[6:7]
	v_lshl_add_u64 v[34:35], v[34:35], 0, v[0:1]
	global_store_dword v[34:35], v30, off
	global_store_dword v[34:35], v31, off offset:512
	global_store_dword v[34:35], v32, off offset:1024
	global_store_dword v[34:35], v33, off offset:1536
	v_add_co_u32_e32 v30, vcc, s64, v34
	s_movk_i32 s0, 0x6000
	s_nop 0
	v_addc_co_u32_e32 v31, vcc, 0, v35, vcc
	global_store_dword v[30:31], v22, off
	global_store_dword v[30:31], v23, off offset:512
	global_store_dword v[30:31], v24, off offset:1024
	global_store_dword v[30:31], v25, off offset:1536
	v_add_co_u32_e32 v22, vcc, s1, v34
	s_nop 1
	v_addc_co_u32_e32 v23, vcc, 0, v35, vcc
	global_store_dword v[22:23], v26, off
	global_store_dword v[22:23], v27, off offset:512
	global_store_dword v[22:23], v28, off offset:1024
	global_store_dword v[22:23], v29, off offset:1536
	v_add_co_u32_e32 v22, vcc, s0, v34
	s_mov_b32 s0, 0x8000
	s_nop 0
	v_addc_co_u32_e32 v23, vcc, 0, v35, vcc
	global_store_dword v[22:23], v14, off
	global_store_dword v[22:23], v15, off offset:512
	global_store_dword v[22:23], v16, off offset:1024
	global_store_dword v[22:23], v17, off offset:1536
	v_add_co_u32_e32 v14, vcc, s0, v34
	s_mov_b32 s0, 0xa000
	s_nop 0
	v_addc_co_u32_e32 v15, vcc, 0, v35, vcc
	global_store_dword v[14:15], v18, off
	global_store_dword v[14:15], v19, off offset:512
	global_store_dword v[14:15], v20, off offset:1024
	global_store_dword v[14:15], v21, off offset:1536
	v_add_co_u32_e32 v14, vcc, s0, v34
	s_nop 1
	v_addc_co_u32_e32 v15, vcc, 0, v35, vcc
	global_store_dword v[14:15], v6, off
	global_store_dword v[14:15], v7, off offset:512
	global_store_dword v[14:15], v8, off offset:1024
	global_store_dword v[14:15], v9, off offset:1536
	v_add_co_u32_e32 v6, vcc, 0xc000, v34
	s_nop 1
	v_addc_co_u32_e32 v7, vcc, 0, v35, vcc
	global_store_dword v[6:7], v10, off
	global_store_dword v[6:7], v11, off offset:512
	global_store_dword v[6:7], v12, off offset:1024
	global_store_dword v[6:7], v13, off offset:1536
	v_add_co_u32_e32 v6, vcc, 0xe000, v34
	s_nop 1
	v_addc_co_u32_e32 v7, vcc, 0, v35, vcc
	global_store_dword v[6:7], v2, off
	global_store_dword v[6:7], v3, off offset:512
	global_store_dword v[6:7], v4, off offset:1024
	global_store_dword v[6:7], v5, off offset:1536
	s_branch .LBB0_1288

.LBB0_1320:
	v_readfirstlane_b32 s67, v107
	s_ashr_i32 s61, s67, 6
	s_lshl_b32 s66, s61, 4
	s_and_b32 s70, s66, 48
	v_or_b32_e32 v129, s70, v109
	v_mul_u32_u24_e32 v0, s49, v129
	s_ashr_i32 s23, s67, 8
	v_lshlrev_b32_e32 v0, 1, v0
	v_lshl_add_u64 v[2:3], s[30:31], 0, v[0:1]
	s_lshl_b32 s30, s23, 6
	s_ashr_i32 s31, s30, 31
	v_mul_lo_u32 v8, s49, v120
	v_lshl_add_u64 v[2:3], s[30:31], 1, v[2:3]
	s_lshl_b32 s31, s61, 10
	s_waitcnt vmcnt(0)
	v_mul_lo_u32 v10, s0, v122
	v_mov_b32_e32 v113, v1
	v_add_lshl_u32 v0, v8, v121, 1
	s_add_i32 s76, s2, s31
	v_lshl_add_u64 v[6:7], v[2:3], 0, v[112:113]
	v_add_lshl_u32 v8, v123, v10, 1
	v_lshl_add_u64 v[10:11], s[34:35], 0, v[0:1]
	s_mov_b32 m0, s76
	v_mul_lo_u32 v9, s0, v120
	global_load_dwordx4 v[2:5], v[6:7], off
	global_load_dwordx4 v[14:17], v[6:7], off offset:64
	s_barrier
	s_add_i32 s0, s76, 0xc000
	global_load_lds_dwordx4 v0, s[34:35]
	v_lshl_add_u64 v[10:11], v[10:11], 0, s[44:45]
	s_add_i32 m0, s76, 0x2000
	v_add_lshl_u32 v6, v9, v121, 1
	global_load_lds_dwordx4 v[10:11], off
	s_mov_b32 m0, s0
	s_add_i32 s0, s59, s31
	global_load_lds_dwordx4 v6, s[36:37]
	s_add_i32 m0, s76, 0xe000
	s_lshl_b32 s74, s49, 7
	global_load_lds_dwordx4 v8, s[36:37]
	s_add_i32 m0, s76, 0x4000
	s_add_u32 s50, s34, s74
	s_addc_u32 s51, s35, 0
	v_mov_b32_e32 v7, v1
	s_waitcnt vmcnt(0)
	v_lshl_add_u64 v[18:19], s[50:51], 0, v[0:1]
	v_lshl_add_u64 v[10:11], s[36:37], 0, v[6:7]
	v_mov_b32_e32 v9, v1
	global_load_lds_dwordx4 v0, s[50:51]
	v_lshl_add_u64 v[18:19], v[18:19], 0, s[44:45]
	s_add_i32 m0, s76, 0x6000
	v_lshl_add_u64 v[12:13], s[36:37], 0, v[8:9]
	global_load_lds_dwordx4 v[18:19], off
	v_lshl_add_u64 v[18:19], v[10:11], 0, s[44:45]
	s_mov_b32 m0, s0
	s_mov_b32 s77, 1
	global_load_lds_dwordx4 v[18:19], off
	v_lshl_add_u64 v[18:19], v[12:13], 0, s[44:45]
	s_add_i32 m0, s0, 0x2000
	s_add_i32 s0, s60, s31
	global_load_lds_dwordx4 v[18:19], off
	s_add_i32 m0, s76, 0x8000
	s_add_u32 s50, s50, s74
	s_addc_u32 s51, s51, 0
	v_lshl_add_u64 v[18:19], s[50:51], 0, v[0:1]
	global_load_lds_dwordx4 v0, s[50:51]
	v_lshl_add_u64 v[18:19], v[18:19], 0, s[44:45]
	s_add_i32 m0, s76, 0xa000
	s_mov_b64 s[50:51], 0x100
	global_load_lds_dwordx4 v[18:19], off
	v_lshl_add_u64 v[10:11], v[10:11], 0, s[50:51]
	s_mov_b32 m0, s0
	s_nop 0
	global_load_lds_dwordx4 v[10:11], off
	v_lshl_add_u64 v[10:11], v[12:13], 0, s[50:51]
	s_add_i32 m0, s0, 0x2000
	s_nop 0
	global_load_lds_dwordx4 v[10:11], off
	v_lshlrev_b32_e32 v10, 16, v2
	v_and_b32_e32 v11, 0xffff0000, v2
	s_mov_b32 s0, 0x3e38aa3b
	v_lshlrev_b32_e32 v2, 16, v3
	v_and_b32_e32 v3, 0xffff0000, v3
	v_pk_mul_f32 v[10:11], v[10:11], s[0:1] op_sel_hi:[1,0]
	v_pk_mul_f32 v[2:3], v[2:3], s[0:1] op_sel_hi:[1,0]
	v_cvt_pk_bf16_f32 v10, v10, v11
	v_cvt_pk_bf16_f32 v11, v2, v3
	v_lshlrev_b32_e32 v2, 16, v4
	v_and_b32_e32 v3, 0xffff0000, v4
	v_pk_mul_f32 v[2:3], v[2:3], s[0:1] op_sel_hi:[1,0]
	s_lshl_b32 s50, s23, 13
	v_cvt_pk_bf16_f32 v12, v2, v3
	v_lshlrev_b32_e32 v2, 16, v5
	v_and_b32_e32 v3, 0xffff0000, v5
	v_pk_mul_f32 v[2:3], v[2:3], s[0:1] op_sel_hi:[1,0]
	s_waitcnt vmcnt(8)
	s_barrier
	v_cvt_pk_bf16_f32 v13, v2, v3
	v_lshlrev_b32_e32 v2, 16, v14
	v_and_b32_e32 v3, 0xffff0000, v14
	v_pk_mul_f32 v[2:3], v[2:3], s[0:1] op_sel_hi:[1,0]
	v_add_u32_e32 v34, s50, v124
	v_cvt_pk_bf16_f32 v18, v2, v3
	v_lshlrev_b32_e32 v2, 16, v15
	v_and_b32_e32 v3, 0xffff0000, v15
	v_pk_mul_f32 v[14:15], v[2:3], s[0:1] op_sel_hi:[1,0]
	ds_read_b128 v[2:5], v34
	ds_read_b128 v[22:25], v34 offset:1024
	v_cvt_pk_bf16_f32 v19, v14, v15
	v_lshlrev_b32_e32 v14, 16, v16
	v_and_b32_e32 v15, 0xffff0000, v16
	v_pk_mul_f32 v[14:15], v[14:15], s[0:1] op_sel_hi:[1,0]
	v_lshlrev_b32_e32 v26, 16, v17
	v_cvt_pk_bf16_f32 v20, v14, v15
	v_and_b32_e32 v27, 0xffff0000, v17
	s_waitcnt lgkmcnt(0)
	v_mfma_f32_16x16x32_bf16 v[2:5], v[2:5], v[10:13], 0
	ds_read_b128 v[14:17], v34 offset:2048
	v_pk_mul_f32 v[26:27], v[26:27], s[0:1] op_sel_hi:[1,0]
	ds_read_b128 v[30:33], v34 offset:6144
	v_cvt_pk_bf16_f32 v21, v26, v27
	ds_read_b128 v[26:29], v34 offset:4096
	s_waitcnt lgkmcnt(0)
	v_mfma_f32_16x16x32_bf16 v[30:33], v[30:33], v[10:13], 0
	s_add_i32 s0, s71, -2
	s_mulk_i32 s49, 0x180
	s_add_u32 s34, s34, s49
	v_mfma_f32_16x16x32_bf16 v[22:25], v[22:25], v[18:21], v[2:5]
	s_addc_u32 s35, s35, 0
	v_lshl_add_u64 v[114:115], s[34:35], 0, v[0:1]
	s_add_u32 s34, s36, 0x180
	ds_read_b128 v[2:5], v34 offset:3072
	v_mfma_f32_16x16x32_bf16 v[14:17], v[14:17], v[10:13], 0
	s_mov_b32 s88, s75
	s_mov_b32 s89, s75
	s_addc_u32 s35, s37, 0
	s_waitcnt lgkmcnt(0)
	v_mfma_f32_16x16x32_bf16 v[14:17], v[2:5], v[18:21], v[14:17]
	ds_read_b128 v[2:5], v34 offset:5120
	ds_read_b128 v[34:37], v34 offset:7168
	s_mov_b32 s90, s75
	v_mfma_f32_16x16x32_bf16 v[26:29], v[26:29], v[10:13], 0
	s_mov_b32 s91, s75
	v_lshl_add_u64 v[118:119], s[34:35], 0, v[6:7]
	v_mov_b32_e32 v6, 0
	s_waitcnt lgkmcnt(0)
	v_mfma_f32_16x16x32_bf16 v[26:29], v[2:5], v[18:21], v[26:29]
	v_mov_b64_e32 v[2:3], s[88:89]
	v_mov_b64_e32 v[4:5], s[90:91]
	v_lshl_add_u64 v[116:117], s[34:35], 0, v[8:9]
	v_mfma_f32_16x16x32_bf16 v[30:33], v[34:37], v[18:21], v[30:33]
	v_max_f32_e32 v34, v25, v25
	v_max_f32_e32 v35, v24, v24
	v_max_f32_e32 v34, v35, v34
	v_max_f32_e32 v35, v17, v17
	v_max_f32_e32 v36, v16, v16
	v_max_f32_e32 v35, v36, v35
	v_max_f32_e32 v36, v27, v27
	v_max_f32_e32 v37, v26, v26
	v_max_f32_e32 v36, v37, v36
	v_max_f32_e32 v37, v29, v29
	v_max_f32_e32 v38, v28, v28
	v_max_f32_e32 v37, v38, v37
	v_max_f32_e32 v38, v33, v33
	v_max_f32_e32 v39, v32, v32
	v_max_f32_e32 v38, v39, v38
	v_max3_f32 v38, v30, v31, v38
	v_max3_f32 v34, v22, v23, v34
	v_max3_f32 v35, v14, v15, v35
	v_max3_f32 v36, v36, v37, v38
	v_max3_f32 v34, v34, v35, v36
	v_mov_b32_e32 v35, v34
	s_nop 1
	v_permlane16_swap_b32_e32 v34, v35
	v_max_f32_e32 v35, v35, v35
	v_max_f32_e32 v34, v34, v34
	v_max_f32_e32 v34, v34, v35
	v_mov_b32_e32 v35, v34
	s_nop 1
	v_permlane32_swap_b32_e32 v34, v35
	v_max_f32_e32 v35, v35, v35
	v_max_f32_e32 v34, v34, v34
	v_max_f32_e32 v113, v34, v35
	v_sub_f32_e32 v74, v22, v113
	v_sub_f32_e32 v22, v26, v113
	v_sub_f32_e32 v26, v30, v113
	v_mov_b32_e32 v30, 0
	v_sub_f32_e32 v77, v25, v113
	v_sub_f32_e32 v76, v24, v113
	v_sub_f32_e32 v75, v23, v113
	v_sub_f32_e32 v73, v17, v113
	v_sub_f32_e32 v72, v16, v113
	v_sub_f32_e32 v71, v15, v113
	v_sub_f32_e32 v70, v14, v113
	v_sub_f32_e32 v25, v29, v113
	v_sub_f32_e32 v24, v28, v113
	v_sub_f32_e32 v23, v27, v113
	v_sub_f32_e32 v29, v33, v113
	v_sub_f32_e32 v28, v32, v113
	v_sub_f32_e32 v27, v31, v113
	v_add_u32_e32 v130, s50, v127
	s_mov_b32 s36, 0
	s_mov_b32 s37, 3
	s_mov_b32 s49, 0
	s_mov_b32 s72, 0
	s_mov_b32 s50, 0
	v_mov_b32_e32 v7, v6
	v_mov_b32_e32 v8, v6
	v_mov_b32_e32 v9, v6
	v_mov_b32_e32 v14, v6
	v_mov_b32_e32 v15, v6
	v_mov_b32_e32 v16, v6
	v_mov_b32_e32 v17, v6
	v_mov_b32_e32 v31, v30
	v_mov_b32_e32 v32, v30
	v_mov_b32_e32 v33, v30
	v_mov_b32_e32 v50, v30
	v_mov_b32_e32 v51, v30
	v_mov_b32_e32 v52, v30
	v_mov_b32_e32 v53, v30
	v_mov_b32_e32 v42, v30
	v_mov_b32_e32 v43, v30
	v_mov_b32_e32 v44, v30
	v_mov_b32_e32 v45, v30
	v_mov_b32_e32 v34, v30
	v_mov_b32_e32 v35, v30
	v_mov_b32_e32 v36, v30
	v_mov_b32_e32 v37, v30
	v_mov_b32_e32 v58, v30
	v_mov_b32_e32 v59, v30
	v_mov_b32_e32 v60, v30
	v_mov_b32_e32 v61, v30
	v_mov_b32_e32 v54, v30
	v_mov_b32_e32 v55, v30
	v_mov_b32_e32 v56, v30
	v_mov_b32_e32 v57, v30
	v_mov_b32_e32 v46, v30
	v_mov_b32_e32 v47, v30
	v_mov_b32_e32 v48, v30
	v_mov_b32_e32 v49, v30
	v_mov_b32_e32 v38, v30
	v_mov_b32_e32 v39, v30
	v_mov_b32_e32 v40, v30
	v_mov_b32_e32 v41, v30
	v_mov_b32_e32 v194, 0
	v_xor_b32_e32 v150, 0x80000000, v113
	v_mov_b32_e32 v154, s48
	v_mov_b32_e32 v151, v150
	v_mov_b32_e32 v155, v154
	v_mov_b32_e32 v152, v150
	v_mov_b32_e32 v156, v154
	v_mov_b32_e32 v153, v150
	v_mov_b32_e32 v157, v154
	s_mov_b64 s[88:89], s[86:87]
	s_cmp_ge_u32 s50, s0
	s_mov_b64 s[34:35], -1
	s_cbranch_scc0 .LBB0_1322

.LBB0_1326:
	s_mul_hi_u32 s34, s77, 0xaaaaaaab
	s_lshr_b32 s34, s34, 1
	s_mul_i32 s34, s34, 0xc000
	v_subrev_u32_e32 v0, s34, v130
	s_add_i32 s34, s2, s36
	v_add_u32_e32 v0, s34, v0
	ds_read_b128 v[188:191], v0
	ds_read_b128 v[82:85], v0 offset:4096
	ds_read_b128 v[94:97], v0 offset:6144
	ds_read_b128 v[98:101], v0 offset:1024
	ds_read_b128 v[86:89], v0 offset:2048
	ds_read_b128 v[132:135], v0 offset:3072
	s_lshl_b32 s34, s49, 14
	v_add_u32_e32 v131, s34, v124
	s_waitcnt lgkmcnt(5)
	v_mfma_f32_16x16x32_bf16 v[188:191], v[188:191], v[10:13], v[150:153]
	ds_read_b128 v[78:81], v0 offset:5120
	s_waitcnt lgkmcnt(2)
	v_mfma_f32_16x16x32_bf16 v[136:139], v[86:89], v[10:13], v[150:153]
	ds_read_b128 v[86:89], v0 offset:7168
	v_mfma_f32_16x16x32_bf16 v[90:93], v[82:85], v[10:13], v[150:153]
	v_mfma_f32_16x16x32_bf16 v[94:97], v[94:97], v[10:13], v[150:153]
	ds_read_b128 v[82:85], v131 offset:49152
	ds_read_b128 v[102:105], v131 offset:51200
	v_mfma_f32_16x16x32_bf16 v[160:163], v[98:101], v[18:21], v[188:191]
	s_waitcnt lgkmcnt(4)
	v_mfma_f32_16x16x32_bf16 v[164:167], v[132:135], v[18:21], v[136:139]
	ds_read_b128 v[98:101], v131 offset:53248
	s_mov_b32 s34, 0x41000000
	v_cmp_lt_f32_e32 vcc, s34, v194
	s_cmp_lg_u64 vcc, 0
	s_cselect_b64 s[34:35], -1, 0
	s_cbranch_vccz .LBB0_1328
	v_cndmask_b32_e32 v132, 0, v194, vcc
	v_exp_f32_e64 v0, -v132
	v_sub_f32_e32 v74, v74, v132
	v_sub_f32_e32 v75, v75, v132
	v_sub_f32_e32 v76, v76, v132
	v_sub_f32_e32 v77, v77, v132
	v_sub_f32_e32 v70, v70, v132
	v_sub_f32_e32 v71, v71, v132
	v_sub_f32_e32 v72, v72, v132
	v_sub_f32_e32 v73, v73, v132
	v_sub_f32_e32 v22, v22, v132
	v_sub_f32_e32 v23, v23, v132
	v_sub_f32_e32 v24, v24, v132
	v_sub_f32_e32 v25, v25, v132
	v_sub_f32_e32 v26, v26, v132
	v_sub_f32_e32 v27, v27, v132
	v_sub_f32_e32 v28, v28, v132
	v_sub_f32_e32 v29, v29, v132
	v_add_f32_e32 v113, v113, v132
	v_xor_b32_e32 v150, 0x80000000, v113
	v_mov_b32_e32 v151, v150
	v_mov_b32_e32 v152, v150
	v_mov_b32_e32 v153, v150
	s_branch .LBB0_1329
.LBB0_1328:
.LBB0_1329:
	ds_read_b128 v[134:137], v131 offset:55296
	s_waitcnt lgkmcnt(5)
	v_mfma_f32_16x16x32_bf16 v[168:171], v[78:81], v[18:21], v[90:93]
	ds_read_b128 v[78:81], v131 offset:57344
	s_waitcnt lgkmcnt(5)
	v_mfma_f32_16x16x32_bf16 v[172:175], v[86:89], v[18:21], v[94:97]
	ds_read_b128 v[86:89], v131 offset:59392
	s_waitcnt lgkmcnt(5)
	v_mfma_f32_16x16x32_bf16 v[30:33], v[82:85], v[14:17], v[30:33]
	v_exp_f32_e32 v145, v74
	v_exp_f32_e32 v146, v75
	v_exp_f32_e32 v147, v76
	v_exp_f32_e32 v148, v77
	ds_read_b128 v[176:179], v131 offset:61440
	s_waitcnt lgkmcnt(5)
	v_mfma_f32_16x16x32_bf16 v[50:53], v[102:105], v[14:17], v[50:53]
	v_max3_f32 v195, v160, v161, v162
	v_max3_f32 v195, v195, v163, v164
	v_max3_f32 v195, v195, v165, v166
	v_max_f32_e32 v195, v195, v167
	ds_read_b128 v[82:85], v131 offset:63488
	s_waitcnt lgkmcnt(5)
	v_mfma_f32_16x16x32_bf16 v[42:45], v[98:101], v[14:17], v[42:45]
	ds_read_b128 v[90:93], v131 offset:50176
	s_waitcnt lgkmcnt(5)
	v_mfma_f32_16x16x32_bf16 v[34:37], v[134:137], v[14:17], v[34:37]
	v_exp_f32_e32 v98, v70
	v_exp_f32_e32 v99, v71
	v_exp_f32_e32 v100, v72
	v_exp_f32_e32 v101, v73
	ds_read_b128 v[180:183], v131 offset:52224
	s_waitcnt lgkmcnt(5)
	v_mfma_f32_16x16x32_bf16 v[58:61], v[78:81], v[14:17], v[58:61]
	v_max3_f32 v194, v168, v169, v170
	v_max3_f32 v194, v194, v171, v172
	v_max3_f32 v194, v194, v173, v174
	v_max3_f32 v194, v194, v175, v195
	ds_read_b128 v[78:81], v131 offset:54272
	s_waitcnt lgkmcnt(5)
	v_mfma_f32_16x16x32_bf16 v[54:57], v[86:89], v[14:17], v[54:57]
	ds_read_b128 v[86:89], v131 offset:56320
	s_waitcnt lgkmcnt(5)
	v_mfma_f32_16x16x32_bf16 v[46:49], v[176:179], v[14:17], v[46:49]
	v_exp_f32_e32 v102, v22
	v_exp_f32_e32 v103, v23
	v_exp_f32_e32 v104, v24
	v_exp_f32_e32 v105, v25
	ds_read_b128 v[176:179], v131 offset:58368
	s_waitcnt lgkmcnt(5)
	v_mfma_f32_16x16x32_bf16 v[38:41], v[82:85], v[14:17], v[38:41]
	v_mfma_f32_16x16x32_bf16 v[2:5], v[154:157], v[14:17], v[2:5]
	v_mov_b32_e32 v158, v194
	s_nop 1
	v_permlane16_swap_b32_e32 v194, v158
	v_max_f32_e32 v194, v194, v158
	ds_read_b128 v[94:97], v131 offset:60416
	s_waitcnt lgkmcnt(5)
	v_mfma_f32_16x16x32_bf16 v[30:33], v[90:93], v[6:9], v[30:33]
	v_exp_f32_e32 v133, v26
	v_exp_f32_e32 v134, v27
	v_exp_f32_e32 v135, v28
	v_exp_f32_e32 v136, v29
	ds_read_b128 v[90:93], v131 offset:62464
	s_waitcnt lgkmcnt(5)
	v_mfma_f32_16x16x32_bf16 v[50:53], v[180:183], v[6:9], v[50:53]
	v_mov_b32_e32 v158, v194
	s_nop 1
	v_permlane32_swap_b32_e32 v194, v158
	v_max_f32_e32 v194, v194, v158
	ds_read_b128 v[180:183], v131 offset:64512
	s_waitcnt lgkmcnt(5)
	v_mfma_f32_16x16x32_bf16 v[42:45], v[78:81], v[6:9], v[42:45]
	s_waitcnt lgkmcnt(4)
	v_mfma_f32_16x16x32_bf16 v[34:37], v[86:89], v[6:9], v[34:37]
	v_cvt_pk_bf16_f32 v14, v145, v146
	v_cvt_pk_bf16_f32 v15, v147, v148
	v_cvt_pk_bf16_f32 v16, v98, v99
	v_cvt_pk_bf16_f32 v17, v100, v101
	v_cvt_pk_bf16_f32 v184, v102, v103
	v_cvt_pk_bf16_f32 v185, v104, v105
	v_cvt_pk_bf16_f32 v186, v133, v134
	v_cvt_pk_bf16_f32 v187, v135, v136
	s_waitcnt lgkmcnt(3)
	v_mfma_f32_16x16x32_bf16 v[58:61], v[176:179], v[6:9], v[58:61]
	s_waitcnt lgkmcnt(2)
	v_mfma_f32_16x16x32_bf16 v[54:57], v[94:97], v[6:9], v[54:57]
	s_waitcnt lgkmcnt(1)
	v_mfma_f32_16x16x32_bf16 v[46:49], v[90:93], v[6:9], v[46:49]
	s_waitcnt lgkmcnt(0)
	v_mfma_f32_16x16x32_bf16 v[38:41], v[180:183], v[6:9], v[38:41]
	v_mfma_f32_16x16x32_bf16 v[2:5], v[154:157], v[6:9], v[2:5]
	s_andn2_b64 vcc, exec, s[34:35]
	s_cbranch_vccnz .LBB0_1331
	v_sub_f32_e32 v160, v160, v132
	v_sub_f32_e32 v161, v161, v132
	v_sub_f32_e32 v162, v162, v132
	v_sub_f32_e32 v163, v163, v132
	v_sub_f32_e32 v164, v164, v132
	v_sub_f32_e32 v165, v165, v132
	v_sub_f32_e32 v166, v166, v132
	v_sub_f32_e32 v167, v167, v132
	v_sub_f32_e32 v168, v168, v132
	v_sub_f32_e32 v169, v169, v132
	v_sub_f32_e32 v170, v170, v132
	v_sub_f32_e32 v171, v171, v132
	v_sub_f32_e32 v172, v172, v132
	v_sub_f32_e32 v173, v173, v132
	v_sub_f32_e32 v174, v174, v132
	v_sub_f32_e32 v175, v175, v132
	v_sub_f32_e32 v194, v194, v132
	v_pk_mul_f32 v[40:41], v[0:1], v[40:41] op_sel_hi:[0,1]
	v_pk_mul_f32 v[48:49], v[0:1], v[48:49] op_sel_hi:[0,1]
	v_pk_mul_f32 v[56:57], v[0:1], v[56:57] op_sel_hi:[0,1]
	v_pk_mul_f32 v[60:61], v[0:1], v[60:61] op_sel_hi:[0,1]
	v_pk_mul_f32 v[36:37], v[0:1], v[36:37] op_sel_hi:[0,1]
	v_pk_mul_f32 v[44:45], v[0:1], v[44:45] op_sel_hi:[0,1]
	v_pk_mul_f32 v[52:53], v[0:1], v[52:53] op_sel_hi:[0,1]
	v_pk_mul_f32 v[32:33], v[0:1], v[32:33] op_sel_hi:[0,1]
	v_pk_mul_f32 v[38:39], v[0:1], v[38:39] op_sel_hi:[0,1]
	v_pk_mul_f32 v[46:47], v[0:1], v[46:47] op_sel_hi:[0,1]
	v_pk_mul_f32 v[54:55], v[0:1], v[54:55] op_sel_hi:[0,1]
	v_pk_mul_f32 v[58:59], v[0:1], v[58:59] op_sel_hi:[0,1]
	v_pk_mul_f32 v[34:35], v[0:1], v[34:35] op_sel_hi:[0,1]
	v_pk_mul_f32 v[42:43], v[0:1], v[42:43] op_sel_hi:[0,1]
	v_pk_mul_f32 v[50:51], v[0:1], v[50:51] op_sel_hi:[0,1]
	v_pk_mul_f32 v[30:31], v[0:1], v[30:31] op_sel_hi:[0,1]
	v_pk_mul_f32 v[4:5], v[0:1], v[4:5] op_sel_hi:[0,1]
	v_pk_mul_f32 v[2:3], v[0:1], v[2:3] op_sel_hi:[0,1]

.Latt_B_1326:
	s_mul_hi_u32 s34, s77, 0xaaaaaaab
	s_lshr_b32 s34, s34, 1
	s_mul_i32 s34, s34, 0xc000
	v_subrev_u32_e32 v0, s34, v130
	s_add_i32 s34, s2, s36
	v_add_u32_e32 v0, s34, v0
	ds_read_b128 v[188:191], v0
	ds_read_b128 v[82:85], v0 offset:4096
	ds_read_b128 v[94:97], v0 offset:6144
	ds_read_b128 v[98:101], v0 offset:1024
	ds_read_b128 v[86:89], v0 offset:2048
	ds_read_b128 v[132:135], v0 offset:3072
	s_lshl_b32 s34, s49, 14
	v_add_u32_e32 v131, s34, v124
	s_waitcnt lgkmcnt(5)
	v_mfma_f32_16x16x32_bf16 v[188:191], v[188:191], v[10:13], v[150:153]
	ds_read_b128 v[78:81], v0 offset:5120
	s_waitcnt lgkmcnt(2)
	v_mfma_f32_16x16x32_bf16 v[136:139], v[86:89], v[10:13], v[150:153]
	ds_read_b128 v[86:89], v0 offset:7168
	v_mfma_f32_16x16x32_bf16 v[90:93], v[82:85], v[10:13], v[150:153]
	v_mfma_f32_16x16x32_bf16 v[94:97], v[94:97], v[10:13], v[150:153]
	ds_read_b128 v[82:85], v131 offset:49152
	ds_read_b128 v[102:105], v131 offset:51200
	v_mfma_f32_16x16x32_bf16 v[74:77], v[98:101], v[18:21], v[188:191]
	s_waitcnt lgkmcnt(4)
	v_mfma_f32_16x16x32_bf16 v[70:73], v[132:135], v[18:21], v[136:139]
	ds_read_b128 v[98:101], v131 offset:53248
	s_mov_b32 s34, 0x41000000
	v_cmp_lt_f32_e32 vcc, s34, v194
	s_cmp_lg_u64 vcc, 0
	s_cselect_b64 s[34:35], -1, 0
	s_cbranch_vccz .Latt_B_1328
	v_cndmask_b32_e32 v132, 0, v194, vcc
	v_exp_f32_e64 v0, -v132
	v_sub_f32_e32 v160, v160, v132
	v_sub_f32_e32 v161, v161, v132
	v_sub_f32_e32 v162, v162, v132
	v_sub_f32_e32 v163, v163, v132
	v_sub_f32_e32 v164, v164, v132
	v_sub_f32_e32 v165, v165, v132
	v_sub_f32_e32 v166, v166, v132
	v_sub_f32_e32 v167, v167, v132
	v_sub_f32_e32 v168, v168, v132
	v_sub_f32_e32 v169, v169, v132
	v_sub_f32_e32 v170, v170, v132
	v_sub_f32_e32 v171, v171, v132
	v_sub_f32_e32 v172, v172, v132
	v_sub_f32_e32 v173, v173, v132
	v_sub_f32_e32 v174, v174, v132
	v_sub_f32_e32 v175, v175, v132
	v_add_f32_e32 v113, v113, v132
	v_xor_b32_e32 v150, 0x80000000, v113
	v_mov_b32_e32 v151, v150
	v_mov_b32_e32 v152, v150
	v_mov_b32_e32 v153, v150
	s_branch .Latt_B_1329
.Latt_B_1328:
.Latt_B_1329:
	ds_read_b128 v[134:137], v131 offset:55296
	s_waitcnt lgkmcnt(5)
	v_mfma_f32_16x16x32_bf16 v[22:25], v[78:81], v[18:21], v[90:93]
	ds_read_b128 v[78:81], v131 offset:57344
	s_waitcnt lgkmcnt(5)
	v_mfma_f32_16x16x32_bf16 v[26:29], v[86:89], v[18:21], v[94:97]
	ds_read_b128 v[86:89], v131 offset:59392
	s_waitcnt lgkmcnt(5)
	v_mfma_f32_16x16x32_bf16 v[30:33], v[82:85], v[14:17], v[30:33]
	v_exp_f32_e32 v145, v160
	v_exp_f32_e32 v146, v161
	v_exp_f32_e32 v147, v162
	v_exp_f32_e32 v148, v163
	ds_read_b128 v[176:179], v131 offset:61440
	s_waitcnt lgkmcnt(5)
	v_mfma_f32_16x16x32_bf16 v[50:53], v[102:105], v[14:17], v[50:53]
	v_max3_f32 v195, v74, v75, v76
	v_max3_f32 v195, v195, v77, v70
	v_max3_f32 v195, v195, v71, v72
	v_max_f32_e32 v195, v195, v73
	ds_read_b128 v[82:85], v131 offset:63488
	s_waitcnt lgkmcnt(5)
	v_mfma_f32_16x16x32_bf16 v[42:45], v[98:101], v[14:17], v[42:45]
	ds_read_b128 v[90:93], v131 offset:50176
	s_waitcnt lgkmcnt(5)
	v_mfma_f32_16x16x32_bf16 v[34:37], v[134:137], v[14:17], v[34:37]
	v_exp_f32_e32 v98, v164
	v_exp_f32_e32 v99, v165
	v_exp_f32_e32 v100, v166
	v_exp_f32_e32 v101, v167
	ds_read_b128 v[180:183], v131 offset:52224
	s_waitcnt lgkmcnt(5)
	v_mfma_f32_16x16x32_bf16 v[58:61], v[78:81], v[14:17], v[58:61]
	v_max3_f32 v194, v22, v23, v24
	v_max3_f32 v194, v194, v25, v26
	v_max3_f32 v194, v194, v27, v28
	v_max3_f32 v194, v194, v29, v195
	ds_read_b128 v[78:81], v131 offset:54272
	s_waitcnt lgkmcnt(5)
	v_mfma_f32_16x16x32_bf16 v[54:57], v[86:89], v[14:17], v[54:57]
	ds_read_b128 v[86:89], v131 offset:56320
	s_waitcnt lgkmcnt(5)
	v_mfma_f32_16x16x32_bf16 v[46:49], v[176:179], v[14:17], v[46:49]
	v_exp_f32_e32 v102, v168
	v_exp_f32_e32 v103, v169
	v_exp_f32_e32 v104, v170
	v_exp_f32_e32 v105, v171
	ds_read_b128 v[176:179], v131 offset:58368
	s_waitcnt lgkmcnt(5)
	v_mfma_f32_16x16x32_bf16 v[38:41], v[82:85], v[14:17], v[38:41]
	v_mfma_f32_16x16x32_bf16 v[2:5], v[154:157], v[14:17], v[2:5]
	v_mov_b32_e32 v158, v194
	s_nop 1
	v_permlane16_swap_b32_e32 v194, v158
	v_max_f32_e32 v194, v194, v158
	ds_read_b128 v[94:97], v131 offset:60416
	s_waitcnt lgkmcnt(5)
	v_mfma_f32_16x16x32_bf16 v[30:33], v[90:93], v[184:187], v[30:33]
	v_exp_f32_e32 v133, v172
	v_exp_f32_e32 v134, v173
	v_exp_f32_e32 v135, v174
	v_exp_f32_e32 v136, v175
	ds_read_b128 v[90:93], v131 offset:62464
	s_waitcnt lgkmcnt(5)
	v_mfma_f32_16x16x32_bf16 v[50:53], v[180:183], v[184:187], v[50:53]
	v_mov_b32_e32 v158, v194
	s_nop 1
	v_permlane32_swap_b32_e32 v194, v158
	v_max_f32_e32 v194, v194, v158
	ds_read_b128 v[180:183], v131 offset:64512
	s_waitcnt lgkmcnt(5)
	v_mfma_f32_16x16x32_bf16 v[42:45], v[78:81], v[184:187], v[42:45]
	s_waitcnt lgkmcnt(4)
	v_mfma_f32_16x16x32_bf16 v[34:37], v[86:89], v[184:187], v[34:37]
	v_cvt_pk_bf16_f32 v14, v145, v146
	v_cvt_pk_bf16_f32 v15, v147, v148
	v_cvt_pk_bf16_f32 v16, v98, v99
	v_cvt_pk_bf16_f32 v17, v100, v101
	v_cvt_pk_bf16_f32 v6, v102, v103
	v_cvt_pk_bf16_f32 v7, v104, v105
	v_cvt_pk_bf16_f32 v8, v133, v134
	v_cvt_pk_bf16_f32 v9, v135, v136
	s_waitcnt lgkmcnt(3)
	v_mfma_f32_16x16x32_bf16 v[58:61], v[176:179], v[184:187], v[58:61]
	s_waitcnt lgkmcnt(2)
	v_mfma_f32_16x16x32_bf16 v[54:57], v[94:97], v[184:187], v[54:57]
	s_waitcnt lgkmcnt(1)
	v_mfma_f32_16x16x32_bf16 v[46:49], v[90:93], v[184:187], v[46:49]
	s_waitcnt lgkmcnt(0)
	v_mfma_f32_16x16x32_bf16 v[38:41], v[180:183], v[184:187], v[38:41]
	v_mfma_f32_16x16x32_bf16 v[2:5], v[154:157], v[184:187], v[2:5]
	s_andn2_b64 vcc, exec, s[34:35]
	s_cbranch_vccnz .Latt_B_1331
	v_sub_f32_e32 v74, v74, v132
	v_sub_f32_e32 v75, v75, v132
	v_sub_f32_e32 v76, v76, v132
	v_sub_f32_e32 v77, v77, v132
	v_sub_f32_e32 v70, v70, v132
	v_sub_f32_e32 v71, v71, v132
	v_sub_f32_e32 v72, v72, v132
	v_sub_f32_e32 v73, v73, v132
	v_sub_f32_e32 v22, v22, v132
	v_sub_f32_e32 v23, v23, v132
	v_sub_f32_e32 v24, v24, v132
	v_sub_f32_e32 v25, v25, v132
	v_sub_f32_e32 v26, v26, v132
	v_sub_f32_e32 v27, v27, v132
	v_sub_f32_e32 v28, v28, v132
	v_sub_f32_e32 v29, v29, v132
	v_sub_f32_e32 v194, v194, v132
	v_pk_mul_f32 v[40:41], v[0:1], v[40:41] op_sel_hi:[0,1]
	v_pk_mul_f32 v[48:49], v[0:1], v[48:49] op_sel_hi:[0,1]
	v_pk_mul_f32 v[56:57], v[0:1], v[56:57] op_sel_hi:[0,1]
	v_pk_mul_f32 v[60:61], v[0:1], v[60:61] op_sel_hi:[0,1]
	v_pk_mul_f32 v[36:37], v[0:1], v[36:37] op_sel_hi:[0,1]
	v_pk_mul_f32 v[44:45], v[0:1], v[44:45] op_sel_hi:[0,1]
	v_pk_mul_f32 v[52:53], v[0:1], v[52:53] op_sel_hi:[0,1]
	v_pk_mul_f32 v[32:33], v[0:1], v[32:33] op_sel_hi:[0,1]
	v_pk_mul_f32 v[38:39], v[0:1], v[38:39] op_sel_hi:[0,1]
	v_pk_mul_f32 v[46:47], v[0:1], v[46:47] op_sel_hi:[0,1]
	v_pk_mul_f32 v[54:55], v[0:1], v[54:55] op_sel_hi:[0,1]
	v_pk_mul_f32 v[58:59], v[0:1], v[58:59] op_sel_hi:[0,1]
	v_pk_mul_f32 v[34:35], v[0:1], v[34:35] op_sel_hi:[0,1]
	v_pk_mul_f32 v[42:43], v[0:1], v[42:43] op_sel_hi:[0,1]
	v_pk_mul_f32 v[50:51], v[0:1], v[50:51] op_sel_hi:[0,1]
	v_pk_mul_f32 v[30:31], v[0:1], v[30:31] op_sel_hi:[0,1]
	v_pk_mul_f32 v[4:5], v[0:1], v[4:5] op_sel_hi:[0,1]
	v_pk_mul_f32 v[2:3], v[0:1], v[2:3] op_sel_hi:[0,1]
